# band attention: first K/V tile prefetch hoisted above the bias-table fill (one load round trip per unit instead of two)
# speedup vs baseline: 1.0018x; 1.0018x over previous
.LBB0_435:
	s_ashr_i32 s16, s92, 31
	s_lshr_b32 s16, s16, 24
	s_add_i32 s23, s92, s16
	s_and_b32 s16, s23, 0xffffff00
	s_sub_i32 s17, s92, s16
	s_bfe_u32 s24, s17, 0x4001b
	s_add_i32 s24, s17, s24
	s_sext_i32_i16 s26, s24
	s_and_b32 s24, s24, 0xfff0
	s_sub_i32 s17, s17, s24
	s_sext_i32_i16 s24, s17
	s_lshl_b32 s17, s26, 7
	s_and_b32 s93, s17, 0xfffff800
	s_add_i32 s16, s93, s16
	v_add_u32_e32 v4, s16, v149
	v_ashrrev_i32_e32 v5, 31, v4
	v_lshlrev_b64 v[122:123], 11, v[4:5]
	s_lshl_b32 s16, s24, 6
	v_lshl_add_u64 v[4:5], s[46:47], 0, v[122:123]
	s_ashr_i32 s17, s16, 31
	v_lshl_add_u64 v[4:5], s[16:17], 1, v[4:5]
	v_lshl_add_u64 v[4:5], v[4:5], 0, v[120:121]
	global_load_dwordx4 v[82:85], v[4:5], off
	global_load_dwordx4 v[86:89], v[4:5], off offset:32
	global_load_dwordx4 v[90:93], v[4:5], off offset:64
	global_load_dwordx4 v[94:97], v[4:5], off offset:96
	s_ashr_i32 s98, s23, 8
	s_lshl_b32 s98, s98, 2
	s_add_i32 s98, s98, -8
	s_cmpk_gt_i32 s92, 0x2ff
	s_cselect_b32 s98, s98, 0
	s_lshl_b32 s98, s98, 6
	s_add_i32 s98, s98, s93
	v_add_u32_e32 v124, s98, v150
	v_ashrrev_i32_e32 v125, 31, v124
	v_lshlrev_b64 v[124:125], 11, v[124:125]
	s_lshl_b64 s[100:101], s[16:17], 1
	v_lshl_add_u64 v[126:127], s[50:51], 0, v[124:125]
	v_lshl_add_u64 v[124:125], s[48:49], 0, v[124:125]
	v_lshl_add_u64 v[126:127], v[126:127], 0, s[100:101]
	v_lshl_add_u64 v[124:125], v[124:125], 0, s[100:101]
	v_lshl_add_u64 v[126:127], v[126:127], 0, v[108:109]
	v_lshl_add_u64 v[124:125], v[124:125], 0, v[108:109]
	global_load_dwordx4 v[98:101], v[126:127], off
	global_load_dwordx4 v[102:105], v[124:125], off
	s_barrier
	s_and_saveexec_b64 s[26:27], s[4:5]
	s_cbranch_execz .LBB0_450
	s_mul_i32 s60, s24, 0x101
	s_mov_b64 s[64:65], -1
	v_mov_b32_e32 v4, v106
	v_mov_b32_e32 v2, v152
	s_and_saveexec_b64 s[62:63], s[8:9]
	s_cbranch_execz .LBB0_447
	v_mov_b32_e32 v7, 0
	v_mov_b64_e32 v[4:5], v[106:107]
	s_and_saveexec_b64 s[64:65], s[10:11]
	s_cbranch_execz .LBB0_441
	s_add_i32 s24, s60, 0x400
	s_add_i32 s94, s60, 0x800
	s_add_i32 s96, s60, 0xc00
	s_mov_b32 s61, s24
	s_mov_b32 s95, s94
	s_mov_b32 s97, s96
	s_mov_b32 s71, 0
	s_mov_b64 s[66:67], 0
	v_mov_b32_e32 v2, v160
	v_mov_b32_e32 v6, v161
	v_mov_b64_e32 v[4:5], v[106:107]

.LBB0_450:
	s_or_b64 exec, exec, s[26:27]
	s_ashr_i32 s23, s23, 8
	s_lshl_b32 s62, s23, 2
	s_add_i32 s23, s62, -8
	s_cmpk_gt_i32 s92, 0x2ff
	s_cselect_b32 s23, s23, 0
	s_or_b32 s24, s62, 3
	s_cmp_le_i32 s23, s24
	s_cbranch_scc0 .LBB0_465
	s_lshl_b32 s60, s23, 6
	s_add_i32 s60, s60, s93
	v_add_u32_e32 v4, s60, v150
	v_ashrrev_i32_e32 v5, 31, v4
	v_lshlrev_b64 v[4:5], 11, v[4:5]
	s_lshl_b64 s[26:27], s[16:17], 1
	v_lshl_add_u64 v[6:7], s[50:51], 0, v[4:5]
	v_lshl_add_u64 v[4:5], s[48:49], 0, v[4:5]
	v_lshl_add_u64 v[6:7], v[6:7], 0, s[26:27]
	v_lshl_add_u64 v[4:5], v[4:5], 0, s[26:27]
	v_lshl_add_u64 v[6:7], v[6:7], 0, v[108:109]
	v_lshl_add_u64 v[4:5], v[4:5], 0, v[108:109]
	s_add_i32 s62, s62, s29
	v_mov_b32_e32 v16, v3
	v_mov_b32_e32 v17, v3
	s_sub_i32 s64, s62, s23
	v_mov_b32_e32 v2, v3
	v_mov_b32_e32 v4, v3
	v_mov_b32_e32 v5, v3
	v_mov_b32_e32 v6, v3
	v_mov_b32_e32 v7, v3
	v_mov_b32_e32 v8, v3
	v_mov_b32_e32 v9, v3
	v_mov_b32_e32 v10, v3
	v_mov_b32_e32 v11, v3
	v_mov_b32_e32 v12, v3
	v_mov_b32_e32 v13, v3
	v_mov_b32_e32 v14, v3
	v_mov_b32_e32 v15, v3
	v_mov_b64_e32 v[48:49], v[16:17]
	v_mov_b64_e32 v[32:33], v[16:17]
	v_lshl_add_u64 v[124:125], v[110:111], 0, s[26:27]
	v_lshl_add_u64 v[126:127], v[112:113], 0, s[26:27]
	s_add_i32 s63, s62, -8
	v_lshl_add_u32 v119, s64, 6, v162
	v_add_u32_e32 v128, s60, v163
	v_mov_b32_e32 v173, 0xf149f2ca
	v_mov_b32_e32 v172, 0
	v_mov_b64_e32 v[46:47], v[14:15]
	v_mov_b64_e32 v[44:45], v[12:13]
	v_mov_b64_e32 v[42:43], v[10:11]
	v_mov_b64_e32 v[40:41], v[8:9]
	v_mov_b64_e32 v[38:39], v[6:7]
	v_mov_b64_e32 v[36:37], v[4:5]
	v_mov_b64_e32 v[34:35], v[2:3]
	v_mov_b64_e32 v[30:31], v[14:15]
	v_mov_b64_e32 v[28:29], v[12:13]
	v_mov_b64_e32 v[26:27], v[10:11]
	v_mov_b64_e32 v[24:25], v[8:9]
	v_mov_b64_e32 v[22:23], v[6:7]
	v_mov_b64_e32 v[20:21], v[4:5]
	v_mov_b64_e32 v[18:19], v[2:3]

	.amdhsa_kernel _Z8yoco_fwd4Args
		.amdhsa_group_segment_fixed_size 0
		.amdhsa_private_segment_fixed_size 0
		.amdhsa_kernarg_size 448
		.amdhsa_user_sgpr_count 2
		.amdhsa_user_sgpr_dispatch_ptr 0
		.amdhsa_user_sgpr_queue_ptr 0
		.amdhsa_user_sgpr_kernarg_segment_ptr 1
		.amdhsa_user_sgpr_dispatch_id 0
		.amdhsa_user_sgpr_kernarg_preload_length 0
		.amdhsa_user_sgpr_kernarg_preload_offset 0
		.amdhsa_user_sgpr_private_segment_size 0
		.amdhsa_uses_dynamic_stack 0
		.amdhsa_enable_private_segment 0
		.amdhsa_system_sgpr_workgroup_id_x 1
		.amdhsa_system_sgpr_workgroup_id_y 0
		.amdhsa_system_sgpr_workgroup_id_z 0
		.amdhsa_system_sgpr_workgroup_info 0
		.amdhsa_system_vgpr_workitem_id 2
		.amdhsa_next_free_vgpr 256
		.amdhsa_next_free_sgpr 102
		.amdhsa_accum_offset 256
		.amdhsa_reserve_vcc 1
		.amdhsa_float_round_mode_32 0
		.amdhsa_float_round_mode_16_64 0
		.amdhsa_float_denorm_mode_32 3
		.amdhsa_float_denorm_mode_16_64 3
		.amdhsa_dx10_clamp 1
		.amdhsa_ieee_mode 1
		.amdhsa_fp16_overflow 0
		.amdhsa_tg_split 0
		.amdhsa_exception_fp_ieee_invalid_op 0
		.amdhsa_exception_fp_denorm_src 0
		.amdhsa_exception_fp_ieee_div_zero 0
		.amdhsa_exception_fp_ieee_overflow 0
		.amdhsa_exception_fp_ieee_underflow 0
		.amdhsa_exception_fp_ieee_inexact 0
		.amdhsa_exception_int_div_zero 0
	.end_amdhsa_kernel

amdhsa.kernels:
  - .agpr_count:     0
    .args:
      - .offset:         0
        .size:           192
        .value_kind:     by_value
      - .offset:         192
        .size:           4
        .value_kind:     hidden_block_count_x
      - .offset:         196
        .size:           4
        .value_kind:     hidden_block_count_y
      - .offset:         200
        .size:           4
        .value_kind:     hidden_block_count_z
      - .offset:         204
        .size:           2
        .value_kind:     hidden_group_size_x
      - .offset:         206
        .size:           2
        .value_kind:     hidden_group_size_y
      - .offset:         208
        .size:           2
        .value_kind:     hidden_group_size_z
      - .offset:         210
        .size:           2
        .value_kind:     hidden_remainder_x
      - .offset:         212
        .size:           2
        .value_kind:     hidden_remainder_y
      - .offset:         214
        .size:           2
        .value_kind:     hidden_remainder_z
      - .offset:         232
        .size:           8
        .value_kind:     hidden_global_offset_x
      - .offset:         240
        .size:           8
        .value_kind:     hidden_global_offset_y
      - .offset:         248
        .size:           8
        .value_kind:     hidden_global_offset_z
      - .offset:         256
        .size:           2
        .value_kind:     hidden_grid_dims
      - .offset:         280
        .size:           8
        .value_kind:     hidden_multigrid_sync_arg
      - .offset:         312
        .size:           4
        .value_kind:     hidden_dynamic_lds_size
    .group_segment_fixed_size: 0
    .kernarg_segment_align: 8
    .kernarg_segment_size: 448
    .language:       OpenCL C
    .language_version:
      - 2
      - 0
    .max_flat_workgroup_size: 512
    .name:           _Z8yoco_fwd4Args
    .private_segment_fixed_size: 0
    .sgpr_count:     108
    .sgpr_spill_count: 0
    .symbol:         _Z8yoco_fwd4Args.kd
    .uniform_work_group_size: 1
    .uses_dynamic_stack: false
    .vgpr_count:     256
    .vgpr_spill_count: 0
    .wavefront_size: 64
